# P2: f32-MFMA block update in the WY solve; stage F KDt block LDS reads batched (no early ticket)
# speedup vs baseline: 1.0039x; 1.0039x over previous
.LBB0_360:
	s_or_b64 exec, exec, s[4:5]
	s_waitcnt lgkmcnt(0)
	s_barrier
	s_and_saveexec_b64 s[4:5], s[44:45]
	s_xor_b64 s[4:5], exec, s[4:5]
	s_cbranch_execz .LBB0_373
	ds_read_b32 v16, v131
	v_lshl_add_u64 v[0:1], s[96:97], 0, v[76:77]
	v_lshl_add_u64 v[18:19], v[0:1], 0, v[78:79]
	ds_read_b128 v[0:3], v183
	ds_read_b128 v[4:7], v183 offset:16
	ds_read_b128 v[8:11], v183 offset:32
	ds_read_b128 v[12:15], v183 offset:48
	s_mov_b64 s[6:7], 0x4400
	s_waitcnt lgkmcnt(3)
	v_lshlrev_b32_e32 v22, 16, v0
	v_and_b32_e32 v23, 0xffff0000, v0
	v_pk_mul_f32 v[22:23], v[16:17], v[22:23] op_sel_hi:[0,1]
	v_cvt_pk_bf16_f32 v0, v22, v23
	v_lshlrev_b32_e32 v22, 16, v1
	v_and_b32_e32 v23, 0xffff0000, v1
	v_pk_mul_f32 v[22:23], v[16:17], v[22:23] op_sel_hi:[0,1]
	v_cvt_pk_bf16_f32 v1, v22, v23
	v_lshlrev_b32_e32 v22, 16, v2
	v_and_b32_e32 v23, 0xffff0000, v2
	v_pk_mul_f32 v[22:23], v[16:17], v[22:23] op_sel_hi:[0,1]
	v_lshl_add_u64 v[20:21], v[18:19], 0, s[6:7]
	v_cvt_pk_bf16_f32 v2, v22, v23
	v_lshlrev_b32_e32 v22, 16, v3
	v_and_b32_e32 v23, 0xffff0000, v3
	s_movk_i32 s6, 0x4000
	v_pk_mul_f32 v[22:23], v[16:17], v[22:23] op_sel_hi:[0,1]
	v_add_co_u32_e32 v18, vcc, s6, v18
	v_cvt_pk_bf16_f32 v3, v22, v23
	s_nop 0
	v_addc_co_u32_e32 v19, vcc, 0, v19, vcc
	global_store_dwordx4 v[18:19], v[0:3], off offset:1024
	s_mov_b64 s[6:7], 0xac00
	s_waitcnt lgkmcnt(2)
	v_lshlrev_b32_e32 v0, 16, v4
	v_and_b32_e32 v1, 0xffff0000, v4
	v_lshlrev_b32_e32 v2, 16, v5
	v_and_b32_e32 v3, 0xffff0000, v5
	v_pk_mul_f32 v[0:1], v[16:17], v[0:1] op_sel_hi:[0,1]
	v_pk_mul_f32 v[2:3], v[16:17], v[2:3] op_sel_hi:[0,1]
	v_cvt_pk_bf16_f32 v0, v0, v1
	v_cvt_pk_bf16_f32 v1, v2, v3
	v_lshlrev_b32_e32 v2, 16, v6
	v_and_b32_e32 v3, 0xffff0000, v6
	v_lshlrev_b32_e32 v4, 16, v7
	v_and_b32_e32 v5, 0xffff0000, v7
	v_pk_mul_f32 v[2:3], v[16:17], v[2:3] op_sel_hi:[0,1]
	v_pk_mul_f32 v[4:5], v[16:17], v[4:5] op_sel_hi:[0,1]
	v_cvt_pk_bf16_f32 v2, v2, v3
	v_cvt_pk_bf16_f32 v3, v4, v5
	global_store_dwordx4 v[20:21], v[0:3], off offset:16
	s_waitcnt lgkmcnt(1)
	v_lshlrev_b32_e32 v4, 16, v11
	v_and_b32_e32 v5, 0xffff0000, v11
	v_lshlrev_b32_e32 v0, 16, v8
	v_and_b32_e32 v1, 0xffff0000, v8
	v_lshlrev_b32_e32 v2, 16, v9
	v_and_b32_e32 v3, 0xffff0000, v9
	v_pk_mul_f32 v[0:1], v[16:17], v[0:1] op_sel_hi:[0,1]
	v_pk_mul_f32 v[2:3], v[16:17], v[2:3] op_sel_hi:[0,1]
	v_cvt_pk_bf16_f32 v0, v0, v1
	v_cvt_pk_bf16_f32 v1, v2, v3
	v_lshlrev_b32_e32 v2, 16, v10
	v_and_b32_e32 v3, 0xffff0000, v10
	v_pk_mul_f32 v[2:3], v[16:17], v[2:3] op_sel_hi:[0,1]
	v_pk_mul_f32 v[4:5], v[16:17], v[4:5] op_sel_hi:[0,1]
	v_cvt_pk_bf16_f32 v2, v2, v3
	v_cvt_pk_bf16_f32 v3, v4, v5
	global_store_dwordx4 v[20:21], v[0:3], off offset:32
	s_waitcnt lgkmcnt(0)
	v_lshlrev_b32_e32 v4, 16, v15
	v_and_b32_e32 v5, 0xffff0000, v15
	v_lshlrev_b32_e32 v0, 16, v12
	v_and_b32_e32 v1, 0xffff0000, v12
	v_lshlrev_b32_e32 v2, 16, v13
	v_and_b32_e32 v3, 0xffff0000, v13
	v_pk_mul_f32 v[0:1], v[16:17], v[0:1] op_sel_hi:[0,1]
	v_pk_mul_f32 v[2:3], v[16:17], v[2:3] op_sel_hi:[0,1]
	v_cvt_pk_bf16_f32 v0, v0, v1
	v_cvt_pk_bf16_f32 v1, v2, v3
	v_lshlrev_b32_e32 v2, 16, v14
	v_and_b32_e32 v3, 0xffff0000, v14
	v_pk_mul_f32 v[2:3], v[16:17], v[2:3] op_sel_hi:[0,1]
	v_pk_mul_f32 v[4:5], v[16:17], v[4:5] op_sel_hi:[0,1]
	v_cvt_pk_bf16_f32 v2, v2, v3
	v_cvt_pk_bf16_f32 v3, v4, v5
	global_store_dwordx4 v[20:21], v[0:3], off offset:48
	s_nop 1
	v_lshl_add_u64 v[0:1], s[96:97], 0, v[82:83]
	v_lshl_add_u64 v[6:7], v[0:1], 0, v[84:85]
	v_lshl_add_u64 v[4:5], v[6:7], 0, s[6:7]
	s_mov_b32 s6, 0xa000
	v_add_co_u32_e32 v6, vcc, s6, v6
	s_nop 1
	v_addc_co_u32_e32 v7, vcc, 0, v7, vcc
	ds_read_u16 v240, v172
	ds_read_u16 v241, v172 offset:272
	ds_read_u16 v242, v173
	ds_read_u16 v243, v172 offset:816
	ds_read_u16 v244, v173 offset:544
	ds_read_u16 v245, v172 offset:1360
	ds_read_u16 v246, v173 offset:1088
	ds_read_u16 v247, v172 offset:1904
	ds_read_b128 v[248:251], v157
	ds_read_b128 v[20:23], v158
	s_waitcnt lgkmcnt(0)
	v_lshlrev_b32_e32 v8, 16, v240
	v_lshlrev_b32_e32 v9, 16, v241
	v_lshlrev_b32_e32 v10, 16, v242
	v_lshlrev_b32_e32 v11, 16, v243
	v_lshlrev_b32_e32 v12, 16, v244
	v_lshlrev_b32_e32 v13, 16, v245
	v_lshlrev_b32_e32 v14, 16, v246
	v_lshlrev_b32_e32 v15, 16, v247
	v_pk_mul_f32 v[8:9], v[248:249], v[8:9]
	v_pk_mul_f32 v[10:11], v[250:251], v[10:11]
	v_pk_mul_f32 v[12:13], v[20:21], v[12:13]
	v_pk_mul_f32 v[14:15], v[22:23], v[14:15]
	ds_read_u16 v240, v173 offset:1632
	ds_read_u16 v241, v172 offset:2448
	ds_read_u16 v242, v173 offset:2176
	ds_read_u16 v243, v172 offset:2992
	ds_read_u16 v244, v173 offset:2720
	ds_read_u16 v245, v172 offset:3536
	ds_read_u16 v246, v173 offset:3264
	ds_read_u16 v247, v172 offset:4080
	ds_read_b128 v[248:251], v159
	ds_read_b128 v[20:23], v160
	v_cvt_pk_bf16_f32 v0, v8, v9
	v_cvt_pk_bf16_f32 v1, v10, v11
	v_cvt_pk_bf16_f32 v2, v12, v13
	v_cvt_pk_bf16_f32 v3, v14, v15
	global_store_dwordx4 v[6:7], v[0:3], off offset:3072
	s_waitcnt lgkmcnt(0)
	v_lshlrev_b32_e32 v8, 16, v240
	v_lshlrev_b32_e32 v9, 16, v241
	v_lshlrev_b32_e32 v10, 16, v242
	v_lshlrev_b32_e32 v11, 16, v243
	v_lshlrev_b32_e32 v12, 16, v244
	v_lshlrev_b32_e32 v13, 16, v245
	v_lshlrev_b32_e32 v14, 16, v246
	v_lshlrev_b32_e32 v15, 16, v247
	v_pk_mul_f32 v[8:9], v[248:249], v[8:9]
	v_pk_mul_f32 v[10:11], v[250:251], v[10:11]
	v_pk_mul_f32 v[12:13], v[20:21], v[12:13]
	v_pk_mul_f32 v[14:15], v[22:23], v[14:15]
	ds_read_u16 v240, v173 offset:3808
	ds_read_u16 v241, v172 offset:4624
	ds_read_u16 v242, v173 offset:4352
	ds_read_u16 v243, v172 offset:5168
	ds_read_u16 v244, v173 offset:4896
	ds_read_u16 v245, v172 offset:5712
	ds_read_u16 v246, v173 offset:5440
	ds_read_u16 v247, v172 offset:6256
	ds_read_b128 v[248:251], v161
	ds_read_b128 v[20:23], v162
	v_cvt_pk_bf16_f32 v0, v8, v9
	v_cvt_pk_bf16_f32 v1, v10, v11
	v_cvt_pk_bf16_f32 v2, v12, v13
	v_cvt_pk_bf16_f32 v3, v14, v15
	global_store_dwordx4 v[4:5], v[0:3], off offset:16
	s_waitcnt lgkmcnt(0)
	v_lshlrev_b32_e32 v8, 16, v240
	v_lshlrev_b32_e32 v9, 16, v241
	v_lshlrev_b32_e32 v10, 16, v242
	v_lshlrev_b32_e32 v11, 16, v243
	v_lshlrev_b32_e32 v12, 16, v244
	v_lshlrev_b32_e32 v13, 16, v245
	v_lshlrev_b32_e32 v14, 16, v246
	v_lshlrev_b32_e32 v15, 16, v247
	v_pk_mul_f32 v[8:9], v[248:249], v[8:9]
	v_pk_mul_f32 v[10:11], v[250:251], v[10:11]
	v_pk_mul_f32 v[12:13], v[20:21], v[12:13]
	v_pk_mul_f32 v[14:15], v[22:23], v[14:15]
	ds_read_u16 v240, v173 offset:5984
	ds_read_u16 v241, v172 offset:6800
	ds_read_u16 v242, v173 offset:6528
	ds_read_u16 v243, v172 offset:7344
	ds_read_u16 v244, v173 offset:7072
	ds_read_u16 v245, v172 offset:7888
	ds_read_u16 v246, v173 offset:7616
	ds_read_u16 v247, v172 offset:8432
	ds_read_b128 v[248:251], v163
	ds_read_b128 v[20:23], v164
	v_cvt_pk_bf16_f32 v0, v8, v9
	v_cvt_pk_bf16_f32 v1, v10, v11
	v_cvt_pk_bf16_f32 v2, v12, v13
	v_cvt_pk_bf16_f32 v3, v14, v15
	global_store_dwordx4 v[4:5], v[0:3], off offset:32
	s_waitcnt lgkmcnt(0)
	v_lshlrev_b32_e32 v8, 16, v240
	v_lshlrev_b32_e32 v9, 16, v241
	v_lshlrev_b32_e32 v10, 16, v242
	v_lshlrev_b32_e32 v11, 16, v243
	v_lshlrev_b32_e32 v12, 16, v244
	v_lshlrev_b32_e32 v13, 16, v245
	v_lshlrev_b32_e32 v14, 16, v246
	v_lshlrev_b32_e32 v15, 16, v247
	v_pk_mul_f32 v[8:9], v[248:249], v[8:9]
	v_pk_mul_f32 v[10:11], v[250:251], v[10:11]
	v_pk_mul_f32 v[12:13], v[20:21], v[12:13]
	v_pk_mul_f32 v[14:15], v[22:23], v[14:15]
	v_cvt_pk_bf16_f32 v0, v8, v9
	v_cvt_pk_bf16_f32 v1, v10, v11
	v_cvt_pk_bf16_f32 v2, v12, v13
	v_cvt_pk_bf16_f32 v3, v14, v15
	global_store_dwordx4 v[4:5], v[0:3], off offset:48
	s_and_saveexec_b64 s[6:7], s[42:43]
	s_cbranch_execz .LBB0_365
	s_mov_b64 s[10:11], exec
	v_mbcnt_lo_u32_b32 v0, s10, 0
	v_mbcnt_hi_u32_b32 v0, s11, v0
	v_cmp_eq_u32_e32 vcc, 0, v0
	s_and_saveexec_b64 s[8:9], vcc
	s_cbranch_execz .LBB0_364
	s_bcnt1_i32_b64 s10, s[10:11]
	v_mov_b32_e32 v1, s10
	v_readlane_b32 s10, v238, 21
	v_readlane_b32 s11, v238, 22
	s_nop 4
	global_atomic_add v1, v81, v1, s[10:11] sc0
